# wout residual epilogue: x loads of all four row groups prefetched two groups ahead into free registers, counted vmcnt
# baseline (speedup 1.0000x reference)
; DI float bf_lo(unsigned u) { return __uint_as_float(u << 16); }
; template <bool XBF, bool WF32>
; DI void resid_epilogue(const float* __restrict__ xs, const bf16_t* __restrict__ xsb, float* __restrict__ out, bf16_t* __restrict__ xbn, float* __restrict__ ssq,
;                        const f32x4 (&acc)[2][2][4][2], int m0, int n0, int nt, bool wxb = true) {
;     ...
; #pragma unroll
;     for (int bj = 0; bj < 2; ++bj)
; #pragma unroll
;         for (int nn = 0; nn < 2; ++nn) {
;             const size_t tok = (size_t)m0 + bj * 128 + wc * 32 + nn * 16 + fr;
;             float ss = 0.f;
; #pragma unroll
;             for (int ai = 0; ai < 2; ++ai) {
;                 float lo[8], hi[8];
;                 grp16(acc, ai, bj, nn, 1.f, lo, hi);
;                 const size_t o = tok * 1024 + n0 + ai * 128 + wr * 64 + 8 * fq;
;                 if (XBF) {
;                     const u32x4 xl = *(const u32x4*)(xsb + o), xh = *(const u32x4*)(xsb + o + 32);
; #pragma unroll
;                     for (int j = 0; j < 4; ++j) { lo[2 * j] += bf_lo(xl[j]); lo[2 * j + 1] += bf_hi(xl[j]); hi[2 * j] += bf_lo(xh[j]); hi[2 * j + 1] += bf_hi(xh[j]); }
;                 } else {
; #pragma unroll
;                     for (int q4 = 0; q4 < 2; ++q4) {
;                         const f32x4 xl = *(const f32x4*)(xs + o + 4 * q4), xh = *(const f32x4*)(xs + o + 32 + 4 * q4);
; #pragma unroll
;                         for (int j = 0; j < 4; ++j) { lo[4 * q4 + j] += xl[j]; hi[4 * q4 + j] += xh[j]; }
;                     }
;                 }
; #pragma unroll
;                 for (int i = 0; i < 8; ++i) ss += lo[i] * lo[i] + hi[i] * hi[i];
;                 if (WF32) {
; #pragma unroll
;                     for (int q4 = 0; q4 < 2; ++q4) {
;                         *(f32x4*)(out + o + 4 * q4) = (f32x4){lo[4 * q4], lo[4 * q4 + 1], lo[4 * q4 + 2], lo[4 * q4 + 3]};
;                         *(f32x4*)(out + o + 32 + 4 * q4) = (f32x4){hi[4 * q4], hi[4 * q4 + 1], hi[4 * q4 + 2], hi[4 * q4 + 3]};
;                     }
;                 }
;                 if (wxb) { st8(xbn + o, lo); st8(xbn + o + 32, hi); }
;             }
;             ss += __shfl_xor(ss, 16); ss += __shfl_xor(ss, 32);
;             if (wxb && fq < 2) ssq[tok * 16 + 4 * nt + 2 * fq + wr] = fq == 0 ? ss : 0.f;
;             __builtin_amdgcn_sched_barrier(0);
;         }
.LBB0_29:
	s_or_b64 exec, exec, s[12:13]
	v_mov_b32_e32 v0, v162
	s_lshl_b32 s12, s27, 8
	v_ashrrev_i32_e32 v150, 8, v0
	v_and_b32_e32 v130, 15, v0
	v_bfe_u32 v133, v0, 4, 2
	v_lshrrev_b32_e32 v0, 1, v0
	v_and_b32_e32 v0, 0x60, v0
	v_or3_b32 v132, v130, s12, v0
	v_lshlrev_b32_e32 v130, 6, v150
	v_ashrrev_i32_e32 v131, 31, v130
	v_lshl_add_u64 v[130:131], v[130:131], 0, s[6:7]
	s_lshl_b32 s6, s26, 2
	s_ashr_i32 s7, s6, 31
	s_lshl_b64 s[6:7], s[6:7], 2
	v_readlane_b32 s12, v253, 32
	v_readlane_b32 s13, v253, 33
	s_add_u32 s6, s12, s6
	v_lshlrev_b32_e32 v0, 3, v133
	s_addc_u32 s7, s13, s7
	v_or_b32_e32 v130, v130, v0
	v_lshl_add_u64 v[152:153], s[6:7], 0, v[0:1]
	v_lshlrev_b32_e32 v0, 10, v132
	v_lshl_add_u64 v[154:155], v[130:131], 0, v[0:1]
	v_lshl_add_u64 v[156:157], v[154:155], 2, s[10:11]
	global_load_dwordx4 v[184:187], v[156:157], off
	global_load_dwordx4 v[188:191], v[156:157], off offset:128
	global_load_dwordx4 v[192:195], v[156:157], off offset:16
	global_load_dwordx4 v[196:199], v[156:157], off offset:144
	global_load_dwordx4 v[200:203], v[156:157], off offset:512
	global_load_dwordx4 v[204:207], v[156:157], off offset:640
	global_load_dwordx4 v[208:211], v[156:157], off offset:528
	global_load_dwordx4 v[212:215], v[156:157], off offset:656
	s_mov_b64 s[0:1], 0x10000
	v_lshl_add_u64 v[248:249], v[156:157], 0, s[0:1]
	s_mov_b64 s[0:1], 0x80000
	v_lshl_add_u64 v[250:251], v[156:157], 0, s[0:1]
	s_mov_b64 s[0:1], 0x90000
	v_lshl_add_u64 v[164:165], v[156:157], 0, s[0:1]
	global_load_dwordx4 v[216:219], v[248:249], off
	global_load_dwordx4 v[220:223], v[248:249], off offset:128
	global_load_dwordx4 v[224:227], v[248:249], off offset:16
	global_load_dwordx4 v[228:231], v[248:249], off offset:144
	global_load_dwordx4 v[232:235], v[248:249], off offset:512
	global_load_dwordx4 v[236:239], v[248:249], off offset:640
	global_load_dwordx4 v[240:243], v[248:249], off offset:528
	global_load_dwordx4 v[244:247], v[248:249], off offset:656
	s_waitcnt vmcnt(12)
	s_nop 1
	v_mov_b64_e32 v[134:135], v[184:185]
	v_mov_b64_e32 v[136:137], v[186:187]
	v_mov_b64_e32 v[138:139], v[188:189]
	v_mov_b64_e32 v[140:141], v[190:191]
	v_mov_b64_e32 v[142:143], v[192:193]
	v_mov_b64_e32 v[144:145], v[194:195]
	v_mov_b64_e32 v[146:147], v[196:197]
	v_mov_b64_e32 v[148:149], v[198:199]
	v_lshl_add_u64 v[154:155], v[154:155], 1, s[8:9]
	v_xor_b32_e32 v0, 16, v176
	v_ashrrev_i32_e32 v151, 31, v150
	v_cmp_gt_u32_e64 s[6:7], 2, v133
	v_pk_add_f32 v[158:159], v[116:117], v[136:137]
	v_pk_add_f32 v[160:161], v[114:115], v[134:135]
	v_pk_add_f32 v[144:145], v[120:121], v[144:145]
	v_pk_add_f32 v[142:143], v[118:119], v[142:143]
	v_pk_add_f32 v[140:141], v[124:125], v[140:141]
	v_pk_add_f32 v[138:139], v[122:123], v[138:139]
	v_pk_add_f32 v[148:149], v[128:129], v[148:149]
	v_pk_add_f32 v[146:147], v[126:127], v[146:147]
	v_cvt_pk_bf16_f32 v114, v160, v161
	v_cvt_pk_bf16_f32 v115, v158, v159
	v_cvt_pk_bf16_f32 v116, v142, v143
	v_cvt_pk_bf16_f32 v117, v144, v145
	v_cvt_pk_bf16_f32 v118, v138, v139
	v_cvt_pk_bf16_f32 v119, v140, v141
	v_cvt_pk_bf16_f32 v120, v146, v147
	v_cvt_pk_bf16_f32 v121, v148, v149
	global_store_dwordx4 v[154:155], v[114:117], off
	global_store_dwordx4 v[154:155], v[118:121], off offset:64
	s_waitcnt vmcnt(10)
	s_nop 1
	v_mov_b64_e32 v[118:119], v[200:201]
	v_mov_b64_e32 v[120:121], v[202:203]
	v_mov_b64_e32 v[122:123], v[204:205]
	v_mov_b64_e32 v[124:125], v[206:207]
	v_mov_b64_e32 v[126:127], v[208:209]
	v_mov_b64_e32 v[128:129], v[210:211]
	v_mov_b64_e32 v[134:135], v[212:213]
	v_mov_b64_e32 v[136:137], v[214:215]
	global_load_dwordx4 v[184:187], v[250:251], off
	global_load_dwordx4 v[188:191], v[250:251], off offset:128
	global_load_dwordx4 v[192:195], v[250:251], off offset:16
	global_load_dwordx4 v[196:199], v[250:251], off offset:144
	global_load_dwordx4 v[200:203], v[250:251], off offset:512
	global_load_dwordx4 v[204:207], v[250:251], off offset:640
	global_load_dwordx4 v[208:211], v[250:251], off offset:528
	global_load_dwordx4 v[212:215], v[250:251], off offset:656
	v_and_b32_e32 v114, 64, v176
	v_add_u32_e32 v114, 64, v114
	v_cmp_lt_i32_e32 vcc, v0, v114
	v_pk_mul_f32 v[138:139], v[138:139], v[138:139]
	v_pk_mul_f32 v[140:141], v[140:141], v[140:141]
	v_cndmask_b32_e32 v0, v176, v0, vcc
	v_pk_fma_f32 v[138:139], v[160:161], v[160:161], v[138:139]
	v_lshlrev_b32_e32 v117, 2, v0
	v_pk_fma_f32 v[140:141], v[158:159], v[158:159], v[140:141]
	v_add_f32_e32 v0, v138, v139
	v_pk_mul_f32 v[146:147], v[146:147], v[146:147]
	v_add_f32_e32 v0, v140, v0
	v_pk_fma_f32 v[142:143], v[142:143], v[142:143], v[146:147]
	v_add_f32_e32 v0, v141, v0
	v_pk_mul_f32 v[148:149], v[148:149], v[148:149]
	v_add_f32_e32 v0, v142, v0
	v_pk_fma_f32 v[144:145], v[144:145], v[144:145], v[148:149]
	v_add_f32_e32 v0, v143, v0
	v_add_f32_e32 v0, v144, v0
	v_add_f32_e32 v0, v145, v0
	v_xor_b32_e32 v115, 32, v176
	v_cmp_lt_i32_e32 vcc, v115, v114
	v_pk_add_f32 v[118:119], v[98:99], v[118:119]
	v_pk_add_f32 v[106:107], v[106:107], v[122:123]
	v_pk_add_f32 v[108:109], v[108:109], v[124:125]
	v_pk_mul_f32 v[122:123], v[106:107], v[106:107]
	v_cvt_pk_bf16_f32 v98, v118, v119
	v_pk_fma_f32 v[118:119], v[118:119], v[118:119], v[122:123]
	v_pk_add_f32 v[100:101], v[100:101], v[120:121]
	v_pk_mul_f32 v[120:121], v[108:109], v[108:109]
	v_add_f32_e32 v0, v118, v0
	v_pk_add_f32 v[112:113], v[112:113], v[136:137]
	v_pk_add_f32 v[110:111], v[110:111], v[134:135]
	v_pk_fma_f32 v[120:121], v[100:101], v[100:101], v[120:121]
	v_add_f32_e32 v0, v119, v0
	v_pk_add_f32 v[104:105], v[104:105], v[128:129]
	v_pk_add_f32 v[102:103], v[102:103], v[126:127]
	v_pk_mul_f32 v[124:125], v[112:113], v[112:113]
	v_pk_mul_f32 v[126:127], v[110:111], v[110:111]
	v_add_f32_e32 v0, v120, v0
	v_pk_fma_f32 v[122:123], v[104:105], v[104:105], v[124:125]
	v_pk_fma_f32 v[124:125], v[102:103], v[102:103], v[126:127]
	v_add_f32_e32 v0, v121, v0
	v_add_f32_e32 v0, v124, v0
	v_add_f32_e32 v0, v125, v0
	v_add_f32_e32 v0, v122, v0
	v_add_f32_e32 v0, v123, v0
	ds_bpermute_b32 v118, v117, v0
	v_cndmask_b32_e32 v114, v176, v115, vcc
	v_cvt_pk_bf16_f32 v99, v100, v101
	v_cvt_pk_bf16_f32 v100, v102, v103
	v_cvt_pk_bf16_f32 v101, v104, v105
	v_lshlrev_b32_e32 v116, 2, v114
	global_store_dwordx4 v[154:155], v[98:101], off offset:256
	v_cmp_eq_u32_e32 vcc, 0, v133
	v_lshl_add_u64 v[114:115], v[150:151], 2, v[152:153]
	s_waitcnt lgkmcnt(0)
	v_add_f32_e32 v98, v0, v118
	ds_bpermute_b32 v99, v116, v98
	v_cvt_pk_bf16_f32 v100, v106, v107
	v_cvt_pk_bf16_f32 v101, v108, v109
	v_cvt_pk_bf16_f32 v102, v110, v111
	v_cvt_pk_bf16_f32 v103, v112, v113
	global_store_dwordx4 v[154:155], v[100:103], off offset:320
	s_and_saveexec_b64 s[12:13], s[6:7]
	s_cbranch_execz .LBB0_31
	v_lshlrev_b32_e32 v0, 6, v132
	v_lshl_add_u64 v[100:101], v[114:115], 0, v[0:1]
	s_waitcnt lgkmcnt(0)
	v_add_f32_e32 v0, v98, v99
	v_cndmask_b32_e32 v0, 0, v0, vcc
	global_store_dword v[100:101], v0, off
; DI float bf_lo(unsigned u) { return __uint_as_float(u << 16); }
; template <bool XBF, bool WF32>
; DI void resid_epilogue(const float* __restrict__ xs, const bf16_t* __restrict__ xsb, float* __restrict__ out, bf16_t* __restrict__ xbn, float* __restrict__ ssq,
;                        const f32x4 (&acc)[2][2][4][2], int m0, int n0, int nt, bool wxb = true) {
;     ...
; #pragma unroll
;     for (int bj = 0; bj < 2; ++bj)
; #pragma unroll
;         for (int nn = 0; nn < 2; ++nn) {
;             const size_t tok = (size_t)m0 + bj * 128 + wc * 32 + nn * 16 + fr;
;             float ss = 0.f;
; #pragma unroll
;             for (int ai = 0; ai < 2; ++ai) {
;                 float lo[8], hi[8];
;                 grp16(acc, ai, bj, nn, 1.f, lo, hi);
;                 const size_t o = tok * 1024 + n0 + ai * 128 + wr * 64 + 8 * fq;
;                 if (XBF) {
;                     const u32x4 xl = *(const u32x4*)(xsb + o), xh = *(const u32x4*)(xsb + o + 32);
; #pragma unroll
;                     for (int j = 0; j < 4; ++j) { lo[2 * j] += bf_lo(xl[j]); lo[2 * j + 1] += bf_hi(xl[j]); hi[2 * j] += bf_lo(xh[j]); hi[2 * j + 1] += bf_hi(xh[j]); }
;                 } else {
; #pragma unroll
;                     for (int q4 = 0; q4 < 2; ++q4) {
;                         const f32x4 xl = *(const f32x4*)(xs + o + 4 * q4), xh = *(const f32x4*)(xs + o + 32 + 4 * q4);
; #pragma unroll
;                         for (int j = 0; j < 4; ++j) { lo[4 * q4 + j] += xl[j]; hi[4 * q4 + j] += xh[j]; }
;                     }
;                 }
; #pragma unroll
;                 for (int i = 0; i < 8; ++i) ss += lo[i] * lo[i] + hi[i] * hi[i];
;                 if (WF32) {
; #pragma unroll
;                     for (int q4 = 0; q4 < 2; ++q4) {
;                         *(f32x4*)(out + o + 4 * q4) = (f32x4){lo[4 * q4], lo[4 * q4 + 1], lo[4 * q4 + 2], lo[4 * q4 + 3]};
;                         *(f32x4*)(out + o + 32 + 4 * q4) = (f32x4){hi[4 * q4], hi[4 * q4 + 1], hi[4 * q4 + 2], hi[4 * q4 + 3]};
;                     }
;                 }
;                 if (wxb) { st8(xbn + o, lo); st8(xbn + o + 32, hi); }
;             }
;             ss += __shfl_xor(ss, 16); ss += __shfl_xor(ss, 32);
;             if (wxb && fq < 2) ssq[tok * 16 + 4 * nt + 2 * fq + wr] = fq == 0 ? ss : 0.f;
;             __builtin_amdgcn_sched_barrier(0);
;         }
.LBB0_31:
	s_or_b64 exec, exec, s[12:13]
	v_or_b32_e32 v98, 16, v132
	v_lshlrev_b32_e32 v0, 10, v98
	v_lshl_add_u64 v[112:113], v[0:1], 0, v[130:131]
	v_lshl_add_u64 v[122:123], v[112:113], 2, s[10:11]
	s_waitcnt vmcnt(16)
	s_nop 1
	v_mov_b64_e32 v[100:101], v[216:217]
	v_mov_b64_e32 v[102:103], v[218:219]
	v_mov_b64_e32 v[104:105], v[220:221]
	v_mov_b64_e32 v[106:107], v[222:223]
	v_mov_b64_e32 v[108:109], v[224:225]
	v_mov_b64_e32 v[110:111], v[226:227]
	v_mov_b64_e32 v[118:119], v[228:229]
	v_mov_b64_e32 v[120:121], v[230:231]
	v_lshl_add_u64 v[112:113], v[112:113], 1, s[8:9]
	v_pk_add_f32 v[102:103], v[84:85], v[102:103]
	v_pk_add_f32 v[100:101], v[82:83], v[100:101]
	v_pk_add_f32 v[110:111], v[88:89], v[110:111]
	v_pk_add_f32 v[108:109], v[86:87], v[108:109]
	v_pk_add_f32 v[106:107], v[92:93], v[106:107]
	v_pk_add_f32 v[104:105], v[90:91], v[104:105]
	v_pk_add_f32 v[120:121], v[96:97], v[120:121]
	v_pk_add_f32 v[118:119], v[94:95], v[118:119]
	v_cvt_pk_bf16_f32 v82, v100, v101
	v_cvt_pk_bf16_f32 v83, v102, v103
	v_cvt_pk_bf16_f32 v84, v108, v109
	v_cvt_pk_bf16_f32 v85, v110, v111
	v_cvt_pk_bf16_f32 v86, v104, v105
	v_cvt_pk_bf16_f32 v87, v106, v107
	v_cvt_pk_bf16_f32 v88, v118, v119
	v_cvt_pk_bf16_f32 v89, v120, v121
	global_store_dwordx4 v[112:113], v[82:85], off
	global_store_dwordx4 v[112:113], v[86:89], off offset:64
	s_waitcnt vmcnt(14)
	s_nop 1
	v_mov_b64_e32 v[82:83], v[232:233]
	v_mov_b64_e32 v[84:85], v[234:235]
	v_mov_b64_e32 v[86:87], v[236:237]
	v_mov_b64_e32 v[88:89], v[238:239]
	v_mov_b64_e32 v[90:91], v[240:241]
	v_mov_b64_e32 v[92:93], v[242:243]
	v_mov_b64_e32 v[94:95], v[244:245]
	v_mov_b64_e32 v[96:97], v[246:247]
	global_load_dwordx4 v[216:219], v[164:165], off
	global_load_dwordx4 v[220:223], v[164:165], off offset:128
	global_load_dwordx4 v[224:227], v[164:165], off offset:16
	global_load_dwordx4 v[228:231], v[164:165], off offset:144
	global_load_dwordx4 v[232:235], v[164:165], off offset:512
	global_load_dwordx4 v[236:239], v[164:165], off offset:640
	global_load_dwordx4 v[240:243], v[164:165], off offset:528
	global_load_dwordx4 v[244:247], v[164:165], off offset:656
	v_pk_mul_f32 v[104:105], v[104:105], v[104:105]
	v_pk_mul_f32 v[106:107], v[106:107], v[106:107]
	v_pk_fma_f32 v[100:101], v[100:101], v[100:101], v[104:105]
	v_pk_fma_f32 v[102:103], v[102:103], v[102:103], v[106:107]
	v_add_f32_e32 v0, v100, v101
	v_pk_mul_f32 v[118:119], v[118:119], v[118:119]
	v_add_f32_e32 v0, v102, v0
	v_pk_fma_f32 v[106:107], v[108:109], v[108:109], v[118:119]
	v_add_f32_e32 v0, v103, v0
	v_pk_mul_f32 v[120:121], v[120:121], v[120:121]
	v_add_f32_e32 v0, v106, v0
	v_pk_fma_f32 v[104:105], v[110:111], v[110:111], v[120:121]
	v_add_f32_e32 v0, v107, v0
	v_add_f32_e32 v0, v104, v0
	v_add_f32_e32 v0, v105, v0
	v_pk_add_f32 v[82:83], v[66:67], v[82:83]
	v_pk_add_f32 v[74:75], v[74:75], v[86:87]
	v_pk_add_f32 v[76:77], v[76:77], v[88:89]
	v_pk_mul_f32 v[86:87], v[74:75], v[74:75]
	v_cvt_pk_bf16_f32 v66, v82, v83
	v_pk_fma_f32 v[82:83], v[82:83], v[82:83], v[86:87]
	v_pk_add_f32 v[68:69], v[68:69], v[84:85]
	v_pk_mul_f32 v[84:85], v[76:77], v[76:77]
	v_add_f32_e32 v0, v82, v0
	v_pk_add_f32 v[80:81], v[80:81], v[96:97]
	v_pk_add_f32 v[78:79], v[78:79], v[94:95]
	v_pk_fma_f32 v[84:85], v[68:69], v[68:69], v[84:85]
	v_add_f32_e32 v0, v83, v0
	v_pk_add_f32 v[72:73], v[72:73], v[92:93]
	v_pk_add_f32 v[70:71], v[70:71], v[90:91]
	v_pk_mul_f32 v[88:89], v[80:81], v[80:81]
	v_pk_mul_f32 v[90:91], v[78:79], v[78:79]
	v_add_f32_e32 v0, v84, v0
	v_pk_fma_f32 v[86:87], v[72:73], v[72:73], v[88:89]
	v_pk_fma_f32 v[88:89], v[70:71], v[70:71], v[90:91]
	v_add_f32_e32 v0, v85, v0
	v_add_f32_e32 v0, v88, v0
	v_add_f32_e32 v0, v89, v0
	v_add_f32_e32 v0, v86, v0
	v_add_f32_e32 v0, v87, v0
	ds_bpermute_b32 v82, v117, v0
	v_cvt_pk_bf16_f32 v67, v68, v69
	v_cvt_pk_bf16_f32 v68, v70, v71
	v_cvt_pk_bf16_f32 v69, v72, v73
	global_store_dwordx4 v[112:113], v[66:69], off offset:256
	v_cvt_pk_bf16_f32 v70, v78, v79
	v_cvt_pk_bf16_f32 v71, v80, v81
	s_waitcnt lgkmcnt(0)
	v_add_f32_e32 v66, v0, v82
	ds_bpermute_b32 v67, v116, v66
	v_cvt_pk_bf16_f32 v68, v74, v75
	v_cvt_pk_bf16_f32 v69, v76, v77
	global_store_dwordx4 v[112:113], v[68:71], off offset:320
	s_and_saveexec_b64 s[12:13], s[6:7]
	s_cbranch_execz .LBB0_33
	v_lshlrev_b32_e32 v0, 6, v98
	v_lshl_add_u64 v[68:69], v[114:115], 0, v[0:1]
	s_waitcnt lgkmcnt(0)
	v_add_f32_e32 v0, v66, v67
	v_cndmask_b32_e32 v0, 0, v0, vcc
	global_store_dword v[68:69], v0, off
; DI float bf_lo(unsigned u) { return __uint_as_float(u << 16); }
; template <bool XBF, bool WF32>
; DI void resid_epilogue(const float* __restrict__ xs, const bf16_t* __restrict__ xsb, float* __restrict__ out, bf16_t* __restrict__ xbn, float* __restrict__ ssq,
;                        const f32x4 (&acc)[2][2][4][2], int m0, int n0, int nt, bool wxb = true) {
;     ...
; #pragma unroll
;     for (int bj = 0; bj < 2; ++bj)
; #pragma unroll
;         for (int nn = 0; nn < 2; ++nn) {
;             const size_t tok = (size_t)m0 + bj * 128 + wc * 32 + nn * 16 + fr;
;             float ss = 0.f;
; #pragma unroll
;             for (int ai = 0; ai < 2; ++ai) {
;                 float lo[8], hi[8];
;                 grp16(acc, ai, bj, nn, 1.f, lo, hi);
;                 const size_t o = tok * 1024 + n0 + ai * 128 + wr * 64 + 8 * fq;
;                 if (XBF) {
;                     const u32x4 xl = *(const u32x4*)(xsb + o), xh = *(const u32x4*)(xsb + o + 32);
; #pragma unroll
;                     for (int j = 0; j < 4; ++j) { lo[2 * j] += bf_lo(xl[j]); lo[2 * j + 1] += bf_hi(xl[j]); hi[2 * j] += bf_lo(xh[j]); hi[2 * j + 1] += bf_hi(xh[j]); }
;                 } else {
; #pragma unroll
;                     for (int q4 = 0; q4 < 2; ++q4) {
;                         const f32x4 xl = *(const f32x4*)(xs + o + 4 * q4), xh = *(const f32x4*)(xs + o + 32 + 4 * q4);
; #pragma unroll
;                         for (int j = 0; j < 4; ++j) { lo[4 * q4 + j] += xl[j]; hi[4 * q4 + j] += xh[j]; }
;                     }
;                 }
; #pragma unroll
;                 for (int i = 0; i < 8; ++i) ss += lo[i] * lo[i] + hi[i] * hi[i];
;                 if (WF32) {
; #pragma unroll
;                     for (int q4 = 0; q4 < 2; ++q4) {
;                         *(f32x4*)(out + o + 4 * q4) = (f32x4){lo[4 * q4], lo[4 * q4 + 1], lo[4 * q4 + 2], lo[4 * q4 + 3]};
;                         *(f32x4*)(out + o + 32 + 4 * q4) = (f32x4){hi[4 * q4], hi[4 * q4 + 1], hi[4 * q4 + 2], hi[4 * q4 + 3]};
;                     }
;                 }
;                 if (wxb) { st8(xbn + o, lo); st8(xbn + o + 32, hi); }
;             }
;             ss += __shfl_xor(ss, 16); ss += __shfl_xor(ss, 32);
;             if (wxb && fq < 2) ssq[tok * 16 + 4 * nt + 2 * fq + wr] = fq == 0 ? ss : 0.f;
;             __builtin_amdgcn_sched_barrier(0);
;         }
.LBB0_33:
	s_or_b64 exec, exec, s[12:13]
	v_or_b32_e32 v66, 0x80, v132
	v_lshlrev_b32_e32 v0, 10, v66
	v_lshl_add_u64 v[84:85], v[0:1], 0, v[130:131]
	v_lshl_add_u64 v[86:87], v[84:85], 2, s[10:11]
	s_waitcnt vmcnt(18)
	s_nop 1
	v_mov_b64_e32 v[68:69], v[184:185]
	v_mov_b64_e32 v[70:71], v[186:187]
	v_mov_b64_e32 v[72:73], v[188:189]
	v_mov_b64_e32 v[74:75], v[190:191]
	v_mov_b64_e32 v[76:77], v[192:193]
	v_mov_b64_e32 v[78:79], v[194:195]
	v_mov_b64_e32 v[80:81], v[196:197]
	v_mov_b64_e32 v[82:83], v[198:199]
	v_lshl_add_u64 v[84:85], v[84:85], 1, s[8:9]
	v_pk_add_f32 v[70:71], v[52:53], v[70:71]
	v_pk_add_f32 v[68:69], v[50:51], v[68:69]
	v_pk_add_f32 v[78:79], v[56:57], v[78:79]
	v_pk_add_f32 v[76:77], v[54:55], v[76:77]
	v_pk_add_f32 v[74:75], v[60:61], v[74:75]
	v_pk_add_f32 v[72:73], v[58:59], v[72:73]
	v_pk_add_f32 v[82:83], v[64:65], v[82:83]
	v_pk_add_f32 v[80:81], v[62:63], v[80:81]
	v_cvt_pk_bf16_f32 v50, v68, v69
	v_cvt_pk_bf16_f32 v51, v70, v71
	v_cvt_pk_bf16_f32 v52, v76, v77
	v_cvt_pk_bf16_f32 v53, v78, v79
	v_cvt_pk_bf16_f32 v54, v72, v73
	v_cvt_pk_bf16_f32 v55, v74, v75
	v_cvt_pk_bf16_f32 v56, v80, v81
	v_cvt_pk_bf16_f32 v57, v82, v83
	global_store_dwordx4 v[84:85], v[50:53], off
	global_store_dwordx4 v[84:85], v[54:57], off offset:64
	s_waitcnt vmcnt(16)
	s_nop 1
	v_mov_b64_e32 v[50:51], v[200:201]
	v_mov_b64_e32 v[52:53], v[202:203]
	v_mov_b64_e32 v[54:55], v[204:205]
	v_mov_b64_e32 v[56:57], v[206:207]
	v_mov_b64_e32 v[58:59], v[208:209]
	v_mov_b64_e32 v[60:61], v[210:211]
	v_mov_b64_e32 v[62:63], v[212:213]
	v_mov_b64_e32 v[64:65], v[214:215]
	v_pk_mul_f32 v[72:73], v[72:73], v[72:73]
	v_pk_mul_f32 v[74:75], v[74:75], v[74:75]
	v_pk_fma_f32 v[68:69], v[68:69], v[68:69], v[72:73]
	v_pk_fma_f32 v[70:71], v[70:71], v[70:71], v[74:75]
	v_add_f32_e32 v0, v68, v69
	v_pk_mul_f32 v[80:81], v[80:81], v[80:81]
	v_add_f32_e32 v0, v70, v0
	v_pk_fma_f32 v[74:75], v[76:77], v[76:77], v[80:81]
	v_add_f32_e32 v0, v71, v0
	v_pk_mul_f32 v[82:83], v[82:83], v[82:83]
	v_add_f32_e32 v0, v74, v0
	v_pk_fma_f32 v[72:73], v[78:79], v[78:79], v[82:83]
	v_add_f32_e32 v0, v75, v0
	v_add_f32_e32 v0, v72, v0
	v_add_f32_e32 v0, v73, v0
	v_pk_add_f32 v[50:51], v[34:35], v[50:51]
	v_pk_add_f32 v[42:43], v[42:43], v[54:55]
	v_pk_add_f32 v[44:45], v[44:45], v[56:57]
	v_pk_mul_f32 v[54:55], v[42:43], v[42:43]
	v_cvt_pk_bf16_f32 v34, v50, v51
	v_pk_fma_f32 v[50:51], v[50:51], v[50:51], v[54:55]
	v_pk_add_f32 v[36:37], v[36:37], v[52:53]
	v_pk_mul_f32 v[52:53], v[44:45], v[44:45]
	v_add_f32_e32 v0, v50, v0
	v_pk_add_f32 v[48:49], v[48:49], v[64:65]
	v_pk_add_f32 v[46:47], v[46:47], v[62:63]
	v_pk_fma_f32 v[52:53], v[36:37], v[36:37], v[52:53]
	v_add_f32_e32 v0, v51, v0
	v_pk_add_f32 v[40:41], v[40:41], v[60:61]
	v_pk_add_f32 v[38:39], v[38:39], v[58:59]
	v_pk_mul_f32 v[56:57], v[48:49], v[48:49]
	v_pk_mul_f32 v[58:59], v[46:47], v[46:47]
	v_add_f32_e32 v0, v52, v0
	v_pk_fma_f32 v[54:55], v[40:41], v[40:41], v[56:57]
	v_pk_fma_f32 v[56:57], v[38:39], v[38:39], v[58:59]
	v_add_f32_e32 v0, v53, v0
	v_add_f32_e32 v0, v56, v0
	v_add_f32_e32 v0, v57, v0
	v_add_f32_e32 v0, v54, v0
	v_add_f32_e32 v0, v55, v0
	ds_bpermute_b32 v50, v117, v0
	v_cvt_pk_bf16_f32 v35, v36, v37
	v_cvt_pk_bf16_f32 v36, v38, v39
	v_cvt_pk_bf16_f32 v37, v40, v41
	global_store_dwordx4 v[84:85], v[34:37], off offset:256
	v_cvt_pk_bf16_f32 v38, v46, v47
	v_cvt_pk_bf16_f32 v39, v48, v49
	s_waitcnt lgkmcnt(0)
	v_add_f32_e32 v34, v0, v50
	ds_bpermute_b32 v35, v116, v34
	v_cvt_pk_bf16_f32 v36, v42, v43
	v_cvt_pk_bf16_f32 v37, v44, v45
	global_store_dwordx4 v[84:85], v[36:39], off offset:320
	s_and_saveexec_b64 s[12:13], s[6:7]
	s_cbranch_execz .LBB0_35
	v_lshlrev_b32_e32 v0, 6, v66
	v_lshl_add_u64 v[36:37], v[114:115], 0, v[0:1]
	s_waitcnt lgkmcnt(0)
	v_add_f32_e32 v0, v34, v35
	v_cndmask_b32_e32 v0, 0, v0, vcc
	global_store_dword v[36:37], v0, off
; DI float bf_lo(unsigned u) { return __uint_as_float(u << 16); }
; template <bool XBF, bool WF32>
; DI void resid_epilogue(const float* __restrict__ xs, const bf16_t* __restrict__ xsb, float* __restrict__ out, bf16_t* __restrict__ xbn, float* __restrict__ ssq,
;                        const f32x4 (&acc)[2][2][4][2], int m0, int n0, int nt, bool wxb = true) {
;     ...
; #pragma unroll
;     for (int bj = 0; bj < 2; ++bj)
; #pragma unroll
;         for (int nn = 0; nn < 2; ++nn) {
;             const size_t tok = (size_t)m0 + bj * 128 + wc * 32 + nn * 16 + fr;
;             float ss = 0.f;
; #pragma unroll
;             for (int ai = 0; ai < 2; ++ai) {
;                 float lo[8], hi[8];
;                 grp16(acc, ai, bj, nn, 1.f, lo, hi);
;                 const size_t o = tok * 1024 + n0 + ai * 128 + wr * 64 + 8 * fq;
;                 if (XBF) {
;                     const u32x4 xl = *(const u32x4*)(xsb + o), xh = *(const u32x4*)(xsb + o + 32);
; #pragma unroll
;                     for (int j = 0; j < 4; ++j) { lo[2 * j] += bf_lo(xl[j]); lo[2 * j + 1] += bf_hi(xl[j]); hi[2 * j] += bf_lo(xh[j]); hi[2 * j + 1] += bf_hi(xh[j]); }
;                 } else {
; #pragma unroll
;                     for (int q4 = 0; q4 < 2; ++q4) {
;                         const f32x4 xl = *(const f32x4*)(xs + o + 4 * q4), xh = *(const f32x4*)(xs + o + 32 + 4 * q4);
; #pragma unroll
;                         for (int j = 0; j < 4; ++j) { lo[4 * q4 + j] += xl[j]; hi[4 * q4 + j] += xh[j]; }
;                     }
;                 }
; #pragma unroll
;                 for (int i = 0; i < 8; ++i) ss += lo[i] * lo[i] + hi[i] * hi[i];
;                 if (WF32) {
; #pragma unroll
;                     for (int q4 = 0; q4 < 2; ++q4) {
;                         *(f32x4*)(out + o + 4 * q4) = (f32x4){lo[4 * q4], lo[4 * q4 + 1], lo[4 * q4 + 2], lo[4 * q4 + 3]};
;                         *(f32x4*)(out + o + 32 + 4 * q4) = (f32x4){hi[4 * q4], hi[4 * q4 + 1], hi[4 * q4 + 2], hi[4 * q4 + 3]};
;                     }
;                 }
;                 if (wxb) { st8(xbn + o, lo); st8(xbn + o + 32, hi); }
;             }
;             ss += __shfl_xor(ss, 16); ss += __shfl_xor(ss, 32);
;             if (wxb && fq < 2) ssq[tok * 16 + 4 * nt + 2 * fq + wr] = fq == 0 ? ss : 0.f;
;             __builtin_amdgcn_sched_barrier(0);
;         }
.LBB0_35:
	s_or_b64 exec, exec, s[12:13]
	v_or_b32_e32 v34, 0x90, v132
	v_lshlrev_b32_e32 v0, 10, v34
	v_lshl_add_u64 v[52:53], v[0:1], 0, v[130:131]
	v_lshl_add_u64 v[54:55], v[52:53], 2, s[10:11]
	s_waitcnt vmcnt(10)
	s_nop 1
	v_mov_b64_e32 v[36:37], v[216:217]
	v_mov_b64_e32 v[38:39], v[218:219]
	v_mov_b64_e32 v[40:41], v[220:221]
	v_mov_b64_e32 v[42:43], v[222:223]
	v_mov_b64_e32 v[44:45], v[224:225]
	v_mov_b64_e32 v[46:47], v[226:227]
	v_mov_b64_e32 v[48:49], v[228:229]
	v_mov_b64_e32 v[50:51], v[230:231]
	v_lshl_add_u64 v[52:53], v[52:53], 1, s[8:9]
	v_pk_add_f32 v[38:39], v[20:21], v[38:39]
	v_pk_add_f32 v[36:37], v[18:19], v[36:37]
	v_pk_add_f32 v[46:47], v[24:25], v[46:47]
	v_pk_add_f32 v[44:45], v[22:23], v[44:45]
	v_pk_add_f32 v[42:43], v[28:29], v[42:43]
	v_pk_add_f32 v[40:41], v[26:27], v[40:41]
	v_pk_add_f32 v[50:51], v[32:33], v[50:51]
	v_pk_add_f32 v[48:49], v[30:31], v[48:49]
	v_cvt_pk_bf16_f32 v18, v36, v37
	v_cvt_pk_bf16_f32 v19, v38, v39
	v_cvt_pk_bf16_f32 v20, v44, v45
	v_cvt_pk_bf16_f32 v21, v46, v47
	v_cvt_pk_bf16_f32 v22, v40, v41
	v_cvt_pk_bf16_f32 v23, v42, v43
	v_cvt_pk_bf16_f32 v24, v48, v49
	v_cvt_pk_bf16_f32 v25, v50, v51
	global_store_dwordx4 v[52:53], v[18:21], off
	global_store_dwordx4 v[52:53], v[22:25], off offset:64
	s_waitcnt vmcnt(8)
	s_nop 1
	v_mov_b64_e32 v[18:19], v[232:233]
	v_mov_b64_e32 v[20:21], v[234:235]
	v_mov_b64_e32 v[22:23], v[236:237]
	v_mov_b64_e32 v[24:25], v[238:239]
	v_mov_b64_e32 v[26:27], v[240:241]
	v_mov_b64_e32 v[28:29], v[242:243]
	v_mov_b64_e32 v[30:31], v[244:245]
	v_mov_b64_e32 v[32:33], v[246:247]
	v_pk_mul_f32 v[40:41], v[40:41], v[40:41]
	v_pk_mul_f32 v[42:43], v[42:43], v[42:43]
	v_pk_fma_f32 v[36:37], v[36:37], v[36:37], v[40:41]
	v_pk_fma_f32 v[38:39], v[38:39], v[38:39], v[42:43]
	v_add_f32_e32 v0, v36, v37
	v_pk_mul_f32 v[48:49], v[48:49], v[48:49]
	v_add_f32_e32 v0, v38, v0
	v_pk_fma_f32 v[42:43], v[44:45], v[44:45], v[48:49]
	v_add_f32_e32 v0, v39, v0
	v_pk_mul_f32 v[50:51], v[50:51], v[50:51]
	v_add_f32_e32 v0, v42, v0
	v_pk_fma_f32 v[40:41], v[46:47], v[46:47], v[50:51]
	v_add_f32_e32 v0, v43, v0
	v_add_f32_e32 v0, v40, v0
	v_add_f32_e32 v0, v41, v0
	v_pk_add_f32 v[18:19], v[2:3], v[18:19]
	v_pk_add_f32 v[10:11], v[10:11], v[22:23]
	v_pk_add_f32 v[12:13], v[12:13], v[24:25]
	v_pk_mul_f32 v[22:23], v[10:11], v[10:11]
	v_cvt_pk_bf16_f32 v2, v18, v19
	v_pk_fma_f32 v[18:19], v[18:19], v[18:19], v[22:23]
	v_pk_add_f32 v[4:5], v[4:5], v[20:21]
	v_pk_mul_f32 v[20:21], v[12:13], v[12:13]
	v_add_f32_e32 v0, v18, v0
	v_pk_add_f32 v[16:17], v[16:17], v[32:33]
	v_pk_add_f32 v[14:15], v[14:15], v[30:31]
	v_pk_fma_f32 v[20:21], v[4:5], v[4:5], v[20:21]
	v_add_f32_e32 v0, v19, v0
	v_pk_add_f32 v[8:9], v[8:9], v[28:29]
	v_pk_add_f32 v[6:7], v[6:7], v[26:27]
	v_pk_mul_f32 v[24:25], v[16:17], v[16:17]
	v_pk_mul_f32 v[26:27], v[14:15], v[14:15]
	v_add_f32_e32 v0, v20, v0
	v_pk_fma_f32 v[22:23], v[8:9], v[8:9], v[24:25]
	v_pk_fma_f32 v[24:25], v[6:7], v[6:7], v[26:27]
	v_add_f32_e32 v0, v21, v0
	v_add_f32_e32 v0, v24, v0
	v_add_f32_e32 v0, v25, v0
	v_add_f32_e32 v0, v22, v0
	v_add_f32_e32 v0, v23, v0
	ds_bpermute_b32 v18, v117, v0
	v_cvt_pk_bf16_f32 v3, v4, v5
	v_cvt_pk_bf16_f32 v4, v6, v7
	v_cvt_pk_bf16_f32 v5, v8, v9
	global_store_dwordx4 v[52:53], v[2:5], off offset:256
	v_cvt_pk_bf16_f32 v6, v14, v15
	v_cvt_pk_bf16_f32 v7, v16, v17
	s_waitcnt lgkmcnt(0)
	v_add_f32_e32 v2, v0, v18
	ds_bpermute_b32 v3, v116, v2
	v_cvt_pk_bf16_f32 v4, v10, v11
	v_cvt_pk_bf16_f32 v5, v12, v13
	global_store_dwordx4 v[52:53], v[4:7], off offset:320
	s_and_saveexec_b64 s[12:13], s[6:7]
	s_cbranch_execz .LBB0_22
	v_lshlrev_b32_e32 v0, 6, v34
	v_lshl_add_u64 v[4:5], v[114:115], 0, v[0:1]
	s_waitcnt lgkmcnt(0)
	v_add_f32_e32 v0, v2, v3
	v_cndmask_b32_e32 v0, 0, v0, vcc
	global_store_dword v[4:5], v0, off
	s_branch .LBB0_22
